# spatial gating unit: the 12 LDS-staging loads issued at the top of the unit so they overlap the drain of the attention stores and the address set-up
# speedup vs baseline: 1.0066x; 1.0066x over previous
.LBB0_964:
	s_cmpk_gt_i32 s92, 0xff
	s_cbranch_scc1 .LBB0_973
	s_add_u32 s76, s74, 0x4b00000
	s_addc_u32 s77, s75, 0
	v_readlane_b32 s26, v253, 19
	v_readlane_b32 s27, v253, 20
	v_lshrrev_b32_e32 v3, 6, v215
	v_lshrrev_b32_e32 v7, 5, v214
	v_and_b32_e32 v8, 31, v214
	v_lshlrev_b32_e32 v8, 4, v8
	v_lshl_add_u32 v9, v3, 4, v7
	v_lshl_add_u32 v4, v9, 9, v8
	s_and_b32 s10, s92, 3
	s_lshl_b32 s11, s10, 16
	v_add_u32_e32 v4, s11, v4
	v_add_u32_e32 v5, 0x1000, v4
	global_load_dwordx4 v[216:219], v4, s[26:27]
	global_load_dwordx4 v[220:223], v4, s[26:27] offset:1024
	global_load_dwordx4 v[224:227], v4, s[26:27] offset:2048
	global_load_dwordx4 v[228:231], v4, s[26:27] offset:3072
	global_load_dwordx4 v[232:235], v5, s[26:27]
	global_load_dwordx4 v[236:239], v5, s[26:27] offset:1024
	global_load_dwordx4 v[240:243], v5, s[26:27] offset:2048
	global_load_dwordx4 v[244:247], v5, s[26:27] offset:3072
	v_lshrrev_b32_e32 v7, 4, v214
	v_and_b32_e32 v8, 15, v214
	v_lshlrev_b32_e32 v8, 4, v8
	v_lshl_add_u32 v9, v3, 4, v7
	s_lshl_b32 s11, s10, 7
	v_add_u32_e32 v9, s11, v9
	v_lshlrev_b32_e32 v9, 14, v9
	s_lshr_b32 s11, s92, 2
	s_lshl_b32 s11, s11, 8
	v_add3_u32 v9, v9, v8, s11
	v_add_u32_e32 v11, 0x10000, v9
	global_load_dwordx4 v[178:181], v9, s[76:77]
	global_load_dwordx4 v[182:185], v11, s[76:77]
	v_add_u32_e32 v9, 0x20000, v9
	v_add_u32_e32 v11, 0x20000, v11
	global_load_dwordx4 v[186:189], v9, s[76:77]
	global_load_dwordx4 v[190:193], v11, s[76:77]
	s_waitcnt vmcnt(12)
	v_mov_b32_e32 v133, 0
	s_add_u32 s2, s74, 0x5300000
	v_mov_b32_e32 v149, v133
	s_addc_u32 s3, s75, 0
	v_readlane_b32 s12, v253, 5
	v_lshl_add_u64 v[0:1], s[74:75], 0, v[148:149]
	s_mov_b64 s[10:11], 0x4b00000
	s_add_u32 s6, s74, 0x1d00000
	s_movk_i32 s4, 0x80
	v_lshlrev_b32_e32 v2, 7, v198
	v_lshlrev_b32_e32 v132, 2, v157
	v_readlane_b32 s16, v253, 9
	v_readlane_b32 s17, v253, 10
	v_readlane_b32 s20, v253, 13
	v_readlane_b32 s26, v253, 19
	v_readlane_b32 s27, v253, 20
	v_lshlrev_b32_e32 v136, 6, v146
	v_lshl_add_u64 v[138:139], v[0:1], 0, s[10:11]
	v_mbcnt_lo_u32_b32 v0, -1, 0
	s_addc_u32 s7, s75, 0
	v_cmp_gt_u32_e64 s[4:5], s4, v215
	v_lshl_add_u64 v[134:135], s[26:27], 0, v[132:133]
	s_mov_b32 s11, 0
	v_lshl_add_u32 v137, v215, 2, 0
	v_lshl_add_u32 v164, v147, 5, 0
	s_lshl_b32 s16, s92, 5
	s_lshl_b32 s17, s96, 5
	s_movk_i32 s20, 0x90
	v_lshlrev_b32_e32 v165, 2, v2
	v_lshlrev_b32_e32 v140, 1, v136
	v_mov_b32_e32 v141, v133
	v_lshlrev_b32_e32 v142, 1, v197
	v_mov_b32_e32 v143, v133
	v_mov_b32_e32 v166, 0x358637bd
	v_lshlrev_b32_e32 v144, 2, v146
	v_mbcnt_hi_u32_b32 v167, -1, v0
	v_readlane_b32 s13, v253, 6
	v_readlane_b32 s14, v253, 7
	v_readlane_b32 s15, v253, 8
	v_readlane_b32 s18, v253, 11
	v_readlane_b32 s19, v253, 12
	v_readlane_b32 s21, v253, 14
	v_readlane_b32 s22, v253, 15
	v_readlane_b32 s23, v253, 16
	v_readlane_b32 s24, v253, 17
	v_readlane_b32 s25, v253, 18
	s_branch .LBB0_967

.LBB0_969:
	s_or_b64 exec, exec, s[14:15]
	s_lshl_b32 s10, s21, 7
	v_add_u32_e32 v168, s10, v136
	v_or_b32_e32 v146, s12, v198
	v_ashrrev_i32_e32 v147, 31, v146
	v_lshlrev_b64 v[148:149], 10, v[146:147]
	v_or_b32_e32 v132, s10, v198
	v_lshl_add_u64 v[148:149], s[2:3], 0, v[148:149]
	s_lshl_b32 s10, s21, 8
	v_lshl_add_u64 v[148:149], v[148:149], 0, s[10:11]
	v_readlane_b32 s36, v253, 21
	v_lshl_add_u64 v[148:149], v[148:149], 0, v[140:141]
	v_lshlrev_b32_e32 v132, 2, v132
	v_readlane_b32 s37, v253, 22
	v_lshl_add_u64 v[148:149], v[148:149], 0, v[142:143]
	v_readlane_b32 s38, v253, 23
	v_readlane_b32 s39, v253, 24
	v_readlane_b32 s40, v253, 25
	v_readlane_b32 s41, v253, 26
	global_load_dword v145, v132, s[36:37]
	global_load_dwordx2 v[162:163], v[148:149], off nt
	global_load_dwordx2 v[160:161], v[148:149], off offset:16 nt
	global_load_dwordx2 v[158:159], v[148:149], off offset:32 nt
	global_load_dwordx2 v[156:157], v[148:149], off offset:48 nt
	global_load_dwordx2 v[154:155], v[148:149], off offset:64 nt
	global_load_dwordx2 v[152:153], v[148:149], off offset:80 nt
	global_load_dwordx2 v[150:151], v[148:149], off offset:96 nt
	s_nop 0
	global_load_dwordx2 v[148:149], v[148:149], off offset:112 nt
	s_waitcnt lgkmcnt(0)
	s_add_u32 s76, s74, 0x4b00000
	s_addc_u32 s77, s75, 0
	v_lshrrev_b32_e32 v0, 6, v215
	v_lshrrev_b32_e32 v1, 5, v214
	v_and_b32_e32 v2, 31, v214
	v_lshlrev_b32_e32 v2, 4, v2
	v_lshl_add_u32 v3, v0, 4, v1
	v_lshl_add_u32 v4, v3, 9, v2
	s_lshl_b32 s10, s21, 16
	v_add_u32_e32 v4, s10, v4
	v_add_u32_e32 v5, 0x1000, v4
	v_mul_u32_u24_e32 v6, 0x210, v3
	v_add_u32_e32 v6, 0x9000, v6
	v_add_u32_e32 v6, v6, v2
	v_lshrrev_b32_e32 v7, 4, v214
	v_and_b32_e32 v8, 15, v214
	v_lshlrev_b32_e32 v8, 4, v8
	v_lshl_add_u32 v9, v0, 4, v7
	v_mul_u32_u24_e32 v10, 0x110, v9
	v_add_u32_e32 v10, 0x400, v10
	v_add_u32_e32 v10, v10, v8
	s_lshl_b32 s10, s21, 7
	v_add_u32_e32 v9, s10, v9
	v_lshlrev_b32_e32 v9, 14, v9
	s_lshl_b32 s10, s12, 1
	v_add3_u32 v9, v9, v8, s10
	v_add_u32_e32 v11, 0x10000, v9
	v_readlane_b32 s42, v253, 27
	v_readlane_b32 s43, v253, 28
	v_readlane_b32 s44, v253, 29
	v_readlane_b32 s45, v253, 30
	v_readlane_b32 s46, v253, 31
	v_readlane_b32 s47, v253, 32
	v_readlane_b32 s48, v253, 33
	v_readlane_b32 s49, v253, 34
	v_readlane_b32 s50, v253, 35
	v_readlane_b32 s51, v253, 36
	s_and_saveexec_b64 s[12:13], s[4:5]
	s_cbranch_execz .LBB0_971
	s_waitcnt vmcnt(0)
	v_mov_b32_e32 v170, v17
	v_mov_b32_e32 v171, v18
	v_mov_b32_e32 v17, v19
	v_pk_add_f32 v[16:17], v[170:171], v[16:17]
	s_nop 0
	v_add_f32_e32 v16, v16, v17
	v_fmamk_f32 v16, v16, 0x3c000000, v166
	v_rsq_f32_e32 v16, v16
	ds_write_b32 v137, v16
